# grid barrier: the last XCD leader bumps all per-XCD generation words directly; other leaders poll their own word (one relay hop removed)
# speedup vs baseline: 1.0581x; 1.0064x over previous
.LBB0_1532:
	s_or_b64 exec, exec, s[24:25]
	s_waitcnt vmcnt(0)
	buffer_inv sc1
	v_readfirstlane_b32 s4, v2
	v_cvt_f32_u32_e32 v2, v0
	v_sub_u32_e32 v3, 0, v0
	v_add_u32_e32 v1, s4, v1
	v_readlane_b32 s4, v254, 55
	v_rcp_iflag_f32_e32 v2, v2
	v_readlane_b32 s5, v254, 56
	s_mov_b64 s[24:25], -1
	v_mul_f32_e32 v2, 0x4f7ffffe, v2
	v_cvt_u32_f32_e32 v2, v2
	v_mul_lo_u32 v3, v3, v2
	v_mul_hi_u32 v3, v2, v3
	v_add_u32_e32 v2, v2, v3
	v_mul_hi_u32 v2, v1, v2
	v_mul_lo_u32 v3, v2, v0
	v_sub_u32_e32 v3, v1, v3
	v_cmp_ge_u32_e32 vcc, v3, v0
	v_add_u32_e32 v4, 1, v2
	v_add_u32_e32 v1, 1, v1
	v_cndmask_b32_e32 v2, v2, v4, vcc
	v_sub_u32_e32 v4, v3, v0
	v_cndmask_b32_e32 v3, v3, v4, vcc
	v_cmp_ge_u32_e32 vcc, v3, v0
	v_add_u32_e32 v3, 1, v2
	s_nop 0
	v_cndmask_b32_e32 v2, v2, v3, vcc
	v_mul_lo_u32 v3, v0, v2
	v_add_u32_e32 v0, v3, v0
	v_cmp_ne_u32_e32 vcc, v1, v0
	v_mov_b64_e32 v[0:1], s[4:5]
	s_and_saveexec_b64 s[4:5], vcc
	s_cbranch_execz .Lbar_last
	v_readlane_b32 s24, v254, 51
	v_readlane_b32 s25, v254, 52
	s_mov_b64 s[28:29], 0
	s_nop 3
	global_load_dword v0, v145, s[24:25] sc1
	s_waitcnt vmcnt(0)
	v_cmp_eq_u32_e32 vcc, v0, v2
	s_and_saveexec_b64 s[24:25], vcc
	s_cbranch_execz .LBB0_1543
	s_mov_b32 s33, 1
	s_branch .LBB0_1536

.LBB0_1538:
	v_readlane_b32 s40, v254, 51
	v_readlane_b32 s41, v254, 52
	s_add_i32 s33, s33, 1
	s_mov_b64 s[42:43], -1
	s_nop 2
	global_load_dword v0, v145, s[40:41] sc1
	s_waitcnt vmcnt(0)
	v_cmp_ne_u32_e32 vcc, v0, v2
	s_orn2_b64 s[40:41], vcc, exec
	s_branch .LBB0_1535

.LBB0_1547:
	s_bcnt1_i32_b64 s4, s[4:5]
	v_mov_b32_e32 v0, s4
	v_readlane_b32 s4, v254, 51
	v_readlane_b32 s5, v254, 52
	s_nop 4
	s_getpc_b64 s[98:99]

.Lbar_last:
	s_or_b64 exec, exec, s[4:5]
	s_add_u32 s28, s52, 0x2400
	s_addc_u32 s29, s53, 0
	global_atomic_add v145, v161, s[28:29]
	global_atomic_add v145, v161, s[28:29] offset:256
	global_atomic_add v145, v161, s[28:29] offset:512
	global_atomic_add v145, v161, s[28:29] offset:768
	global_atomic_add v145, v161, s[28:29] offset:1024
	global_atomic_add v145, v161, s[28:29] offset:1280
	global_atomic_add v145, v161, s[28:29] offset:1536
	global_atomic_add v145, v161, s[28:29] offset:1792
	global_atomic_add v145, v161, s[28:29] offset:2048
	global_atomic_add v145, v161, s[28:29] offset:2304
	global_atomic_add v145, v161, s[28:29] offset:2560
	global_atomic_add v145, v161, s[28:29] offset:2816
	global_atomic_add v145, v161, s[28:29] offset:3072
	global_atomic_add v145, v161, s[28:29] offset:3328
	global_atomic_add v145, v161, s[28:29] offset:3584
	global_atomic_add v145, v161, s[28:29] offset:3840
	s_mov_b64 s[24:25], 0
	s_branch .LBB0_1544
